# baseline (speedup 1.0000x reference)
; #define MFMA(a, b, c) __builtin_amdgcn_mfma_f32_32x32x16_bf16((a), (b), (c), 0, 0, 0)
; DI void qk_acc(f32x16 (&st)[2], const bf16x8 (&qf)[4], const char* sb, const int (&foff)[4]) {
; #pragma unroll
;   for (int kb = 0; kb < 2; ++kb)
; #pragma unroll
;     for (int ks = 0; ks < 4; ++ks) {
;       const bf16x8 kf = *(const bf16x8*)(sb + kb * 4096 + foff[ks]);
;       st[kb] = MFMA(kf, qf[ks], st[kb]);
;     }
; }
; template <int DV, bool SEL, bool TERM> ...
;     ...
;     const int dmax = wq_max - kp_mul * k0, dmin = wq_min - kp_mul * (k0 + 63);
;     const bool relevant = !(dmax < 0 || dmin >= W) && !(TERM && done);
;     const float dbase = (float)(tqp - kp_mul * (k0 + 4 * h));
;     f32x16 st[2];
;     if (relevant) {
;       const float tb = -slope2 * dbase - mref;
; #pragma unroll
;       for (int kb = 0; kb < 2; ++kb)
; #pragma unroll
;         for (int i = 0; i < 16; ++i) st[kb][i] = __builtin_fmaf(sk, (float)(kb * 32 + (i & 3) + 8 * (i >> 2)), tb);
;       qk_acc(st, qf, sb, foff);
.LBB0_826:
	s_mul_hi_u32 s0, s19, 0xaaaaaaab
	s_lshr_b32 s1, s0, 1
	s_lshl_b32 s0, s20, 10
	s_add_i32 s6, s0, s63
	s_sub_i32 s10, s62, s0
	s_sub_i32 s11, 0x1bd1, s6
	s_cmp_gt_i32 s10, -1
	s_cselect_b64 s[6:7], -1, 0
	s_cmp_lt_i32 s11, 0x20000000
	v_or_b32_e32 v0, s0, v123
	s_cselect_b64 s[22:23], -1, 0
	v_sub_u32_e32 v18, v114, v0
	s_and_b64 s[6:7], s[6:7], s[22:23]
	v_cmp_eq_u32_e32 vcc, 0, v132
	v_cvt_f32_i32_e32 v0, v18
	s_and_b64 s[22:23], s[6:7], vcc
	v_cndmask_b32_e64 v19, 0, 1, s[22:23]
	v_cmp_ne_u32_e64 s[6:7], 1, v19
	s_andn2_b64 vcc, exec, s[22:23]
	s_mul_i32 s1, s1, 0xffff4000
	s_cbranch_vccnz .LBB0_828
	s_add_i32 s21, s16, s1
	v_add_u32_e32 v19, s21, v129
	ds_read_b128 v[20:23], v19
	s_mov_b32 s22, 2.0
	v_fma_f32 v24, -v182, v0, -v108
	s_mov_b32 s23, 0x40400000
	v_fma_f32 v4, v82, s22, v24
	v_fma_f32 v5, v83, s23, v24
	s_mov_b32 s22, 0x41200000
	s_mov_b32 s23, 0x41300000
	v_fma_f32 v8, v82, s22, v24
	v_fma_f32 v9, v83, s23, v24
	s_mov_b32 s22, 0x41800000
	s_mov_b32 s23, 0x41880000
	v_fma_f32 v2, 0, v82, v24
	v_add_f32_e32 v3, v82, v24
	v_fma_f32 v6, v82, s64, v24
	v_fma_f32 v7, v83, s65, v24
	v_fma_f32 v10, v82, s22, v24
	v_fma_f32 v11, v83, s23, v24
	v_fma_f32 v12, v82, s68, v24
	v_fma_f32 v13, v83, s69, v24
	v_fma_f32 v14, v82, s70, v24
	v_fma_f32 v15, v83, s71, v24
	v_fma_f32 v16, v82, s72, v24
	v_fma_f32 v17, v83, s73, v24
	v_add_u32_e32 v25, s21, v131
	v_add_u32_e32 v26, s21, v130
	s_waitcnt lgkmcnt(0)
	v_mfma_f32_32x32x16_bf16 v[2:17], v[20:23], v[160:163], v[2:17]
	ds_read_b128 v[20:23], v25
	v_add_u32_e32 v27, s21, v128
	v_fma_f32 v78, v102, s74, v24
	v_fma_f32 v79, v103, s75, v24
	v_fma_f32 v76, v100, s76, v24
	v_fma_f32 v77, v101, s77, v24
	v_fma_f32 v74, v98, s78, v24
	v_fma_f32 v75, v99, s79, v24
	v_fma_f32 v72, v96, s80, v24
	v_fma_f32 v73, v97, s81, v24
	v_fma_f32 v70, v94, s82, v24
	v_fma_f32 v71, v95, s83, v24
	s_waitcnt lgkmcnt(0)
	v_mfma_f32_32x32x16_bf16 v[2:17], v[20:23], v[164:167], v[2:17]
	ds_read_b128 v[20:23], v26
	v_fma_f32 v68, v92, s84, v24
	v_fma_f32 v69, v93, s85, v24
	v_fma_f32 v66, v90, s86, v24
	v_fma_f32 v67, v91, s87, v24
	v_fma_f32 v64, v88, s88, v24
	v_fma_f32 v65, v89, s89, v24
	s_waitcnt lgkmcnt(0)
	v_mfma_f32_32x32x16_bf16 v[2:17], v[20:23], v[168:171], v[2:17]
	ds_read_b128 v[20:23], v27
	s_waitcnt lgkmcnt(0)
	v_mfma_f32_32x32x16_bf16 v[2:17], v[20:23], v[172:175], v[2:17]
	ds_read_b128 v[20:23], v19 offset:4096
	s_waitcnt lgkmcnt(0)
	v_mfma_f32_32x32x16_bf16 v[64:79], v[20:23], v[160:163], v[64:79]
	ds_read_b128 v[20:23], v25 offset:4096
	s_waitcnt lgkmcnt(0)
	v_mfma_f32_32x32x16_bf16 v[64:79], v[20:23], v[164:167], v[64:79]
	ds_read_b128 v[20:23], v26 offset:4096
	s_waitcnt lgkmcnt(0)
	v_mfma_f32_32x32x16_bf16 v[64:79], v[20:23], v[168:171], v[64:79]
	ds_read_b128 v[20:23], v27 offset:4096
	s_waitcnt lgkmcnt(0)
	v_mfma_f32_32x32x16_bf16 v[64:79], v[20:23], v[172:175], v[64:79]

; #define MFMA(a, b, c) __builtin_amdgcn_mfma_f32_32x32x16_bf16((a), (b), (c), 0, 0, 0)
; DI void qk_acc(f32x16 (&st)[2], const bf16x8 (&qf)[4], const char* sb, const int (&foff)[4]) {
; #pragma unroll
;   for (int kb = 0; kb < 2; ++kb)
; #pragma unroll
;     for (int ks = 0; ks < 4; ++ks) {
;       const bf16x8 kf = *(const bf16x8*)(sb + kb * 4096 + foff[ks]);
;       st[kb] = MFMA(kf, qf[ks], st[kb]);
;     }
; }
; template <int DV, bool SEL, bool TERM> ...
;     ...
;     const int dmax = wq_max - kp_mul * k0, dmin = wq_min - kp_mul * (k0 + 63);
;     const bool relevant = !(dmax < 0 || dmin >= W) && !(TERM && done);
;     const float dbase = (float)(tqp - kp_mul * (k0 + 4 * h));
;     f32x16 st[2];
;     if (relevant) {
;       const float tb = -slope2 * dbase - mref;
; #pragma unroll
;       for (int kb = 0; kb < 2; ++kb)
; #pragma unroll
;         for (int i = 0; i < 16; ++i) st[kb][i] = __builtin_fmaf(sk, (float)(kb * 32 + (i & 3) + 8 * (i >> 2)), tb);
;       qk_acc(st, qf, sb, foff);
.LBB0_942:
	s_mul_hi_u32 s0, s17, 0xaaaaaaab
	s_lshr_b32 s0, s0, 1
	s_mul_i32 s0, s0, 3
	s_lshl_b32 s19, s8, 6
	s_sub_i32 s0, s17, s0
	s_or_b32 s1, s19, 63
	s_lshl_b32 s20, s0, 14
	s_sub_i32 s0, s12, s19
	s_sub_i32 s1, s62, s1
	s_cmp_gt_i32 s0, -1
	s_cselect_b64 s[6:7], -1, 0
	s_cmp_lt_i32 s1, 0x20000000
	v_or_b32_e32 v0, s19, v251
	s_cselect_b64 s[22:23], -1, 0
	v_sub_u32_e32 v2, v227, v0
	s_and_b64 s[6:7], s[6:7], s[22:23]
	v_cmp_eq_u32_e32 vcc, 0, v253
	v_cvt_f32_i32_e32 v0, v2
	s_and_b64 s[22:23], s[6:7], vcc
	v_cndmask_b32_e64 v3, 0, 1, s[22:23]
	v_cmp_ne_u32_e64 s[6:7], 1, v3
	s_andn2_b64 vcc, exec, s[22:23]
	s_cbranch_vccnz .LBB0_944
	v_add_u32_e32 v3, s20, v242
	ds_read_b128 v[4:7], v3
	s_mov_b32 s22, 2.0
	v_fma_f32 v8, -v182, v0, -v252
	s_mov_b32 s23, 0x40400000
	v_fma_f32 v130, v182, s22, v8
	v_fma_f32 v131, v183, s23, v8
	s_mov_b32 s22, 0x41200000
	s_mov_b32 s23, 0x41300000
	v_fma_f32 v134, v182, s22, v8
	v_fma_f32 v135, v183, s23, v8
	s_mov_b32 s22, 0x41800000
	s_mov_b32 s23, 0x41880000
	v_fma_f32 v128, 0, v182, v8
	v_add_f32_e32 v129, v182, v8
	v_fma_f32 v132, v182, s64, v8
	v_fma_f32 v133, v183, s65, v8
	v_fma_f32 v136, v182, s22, v8
	v_fma_f32 v137, v183, s23, v8
	v_fma_f32 v138, v182, s68, v8
	v_fma_f32 v139, v183, s69, v8
	v_fma_f32 v140, v182, s70, v8
	v_fma_f32 v141, v183, s71, v8
	v_fma_f32 v142, v182, s72, v8
	v_fma_f32 v143, v183, s73, v8
	v_add_u32_e32 v9, s20, v243
	v_add_u32_e32 v10, s20, v244
	s_waitcnt lgkmcnt(0)
	v_mfma_f32_32x32x16_bf16 v[128:143], v[4:7], v[160:163], v[128:143]
	ds_read_b128 v[4:7], v9
	v_add_u32_e32 v11, s20, v245
	v_fma_f32 v158, v204, s74, v8
	v_fma_f32 v159, v205, s75, v8
	v_fma_f32 v156, v202, s76, v8
	v_fma_f32 v157, v203, s77, v8
	v_fma_f32 v154, v200, s78, v8
	v_fma_f32 v155, v201, s79, v8
	v_fma_f32 v152, v198, s80, v8
	v_fma_f32 v153, v199, s81, v8
	v_fma_f32 v150, v196, s82, v8
	v_fma_f32 v151, v197, s83, v8
	s_waitcnt lgkmcnt(0)
	v_mfma_f32_32x32x16_bf16 v[128:143], v[4:7], v[164:167], v[128:143]
	ds_read_b128 v[4:7], v10
	v_fma_f32 v148, v194, s84, v8
	v_fma_f32 v149, v195, s85, v8
	v_fma_f32 v146, v192, s86, v8
	v_fma_f32 v147, v193, s87, v8
	v_fma_f32 v144, v190, s88, v8
	v_fma_f32 v145, v191, s89, v8
	s_waitcnt lgkmcnt(0)
	v_mfma_f32_32x32x16_bf16 v[128:143], v[4:7], v[168:171], v[128:143]
	ds_read_b128 v[4:7], v11
	s_waitcnt lgkmcnt(0)
	v_mfma_f32_32x32x16_bf16 v[128:143], v[4:7], v[172:175], v[128:143]
	ds_read_b128 v[4:7], v3 offset:4096
	s_waitcnt lgkmcnt(0)
	v_mfma_f32_32x32x16_bf16 v[144:159], v[4:7], v[160:163], v[144:159]
	ds_read_b128 v[4:7], v9 offset:4096
	s_waitcnt lgkmcnt(0)
	v_mfma_f32_32x32x16_bf16 v[144:159], v[4:7], v[164:167], v[144:159]
	ds_read_b128 v[4:7], v10 offset:4096
	s_waitcnt lgkmcnt(0)
	v_mfma_f32_32x32x16_bf16 v[144:159], v[4:7], v[168:171], v[144:159]
	ds_read_b128 v[4:7], v11 offset:4096
	s_waitcnt lgkmcnt(0)
	v_mfma_f32_32x32x16_bf16 v[144:159], v[4:7], v[172:175], v[144:159]

; #define MFMA(a, b, c) __builtin_amdgcn_mfma_f32_32x32x16_bf16((a), (b), (c), 0, 0, 0)
; DI void qk_acc(f32x16 (&st)[2], const bf16x8 (&qf)[4], const char* sb, const int (&foff)[4]) {
; #pragma unroll
;   for (int kb = 0; kb < 2; ++kb)
; #pragma unroll
;     for (int ks = 0; ks < 4; ++ks) {
;       const bf16x8 kf = *(const bf16x8*)(sb + kb * 4096 + foff[ks]);
;       st[kb] = MFMA(kf, qf[ks], st[kb]);
;     }
; }
; template <int DV, bool SEL, bool TERM> ...
;     ...
;     const int dmax = wq_max - kp_mul * k0, dmin = wq_min - kp_mul * (k0 + 63);
;     const bool relevant = !(dmax < 0 || dmin >= W) && !(TERM && done);
;     const float dbase = (float)(tqp - kp_mul * (k0 + 4 * h));
;     f32x16 st[2];
;     if (relevant) {
;       const float tb = -slope2 * dbase - mref;
; #pragma unroll
;       for (int kb = 0; kb < 2; ++kb)
; #pragma unroll
;         for (int i = 0; i < 16; ++i) st[kb][i] = __builtin_fmaf(sk, (float)(kb * 32 + (i & 3) + 8 * (i >> 2)), tb);
;       qk_acc(st, qf, sb, foff);
.LBB0_974:
	s_mul_hi_u32 s0, s19, 0xaaaaaaab
	s_lshr_b32 s1, s0, 1
	s_lshl_b32 s0, s13, 6
	s_or_b32 s6, s0, 63
	s_sub_i32 s10, s12, s0
	s_sub_i32 s11, s62, s6
	s_cmp_gt_i32 s10, -1
	s_cselect_b64 s[6:7], -1, 0
	s_cmpk_lt_i32 s11, 0x200
	v_or_b32_e32 v0, s0, v202
	s_cselect_b64 s[20:21], -1, 0
	v_sub_u32_e32 v18, v227, v0
	s_and_b64 s[6:7], s[6:7], s[20:21]
	v_cmp_eq_u32_e32 vcc, 0, v239
	v_cvt_f32_i32_e32 v0, v18
	s_and_b64 s[20:21], s[6:7], vcc
	v_cndmask_b32_e64 v19, 0, 1, s[20:21]
	v_cmp_ne_u32_e64 s[6:7], 1, v19
	s_andn2_b64 vcc, exec, s[20:21]
	s_mul_i32 s1, s1, 0xffff4000
	s_cbranch_vccnz .LBB0_976
	s_add_i32 s13, s18, s1
	v_add_u32_e32 v19, s13, v235
	ds_read_b128 v[20:23], v19
	s_mov_b32 s20, 2.0
	v_fma_f32 v24, -v182, v0, -v238
	s_mov_b32 s21, 0x40400000
	v_fma_f32 v4, v182, s20, v24
	v_fma_f32 v5, v183, s21, v24
	s_mov_b32 s20, 0x41200000
	s_mov_b32 s21, 0x41300000
	v_fma_f32 v8, v182, s20, v24
	v_fma_f32 v9, v183, s21, v24
	s_mov_b32 s20, 0x41800000
	s_mov_b32 s21, 0x41880000
	v_fma_f32 v2, 0, v182, v24
	v_add_f32_e32 v3, v182, v24
	v_fma_f32 v6, v182, s64, v24
	v_fma_f32 v7, v183, s65, v24
	v_fma_f32 v10, v182, s20, v24
	v_fma_f32 v11, v183, s21, v24
	v_fma_f32 v12, v182, s68, v24
	v_fma_f32 v13, v183, s69, v24
	v_fma_f32 v14, v182, s70, v24
	v_fma_f32 v15, v183, s71, v24
	v_fma_f32 v16, v182, s72, v24
	v_fma_f32 v17, v183, s73, v24
	v_add_u32_e32 v25, s13, v237
	v_add_u32_e32 v26, s13, v236
	s_waitcnt lgkmcnt(0)
	v_mfma_f32_32x32x16_bf16 v[2:17], v[20:23], v[160:163], v[2:17]
	ds_read_b128 v[20:23], v25
	v_add_u32_e32 v27, s13, v234
	v_fma_f32 v142, v188, s74, v24
	v_fma_f32 v143, v189, s75, v24
	v_fma_f32 v140, v186, s76, v24
	v_fma_f32 v141, v187, s77, v24
	v_fma_f32 v138, v184, s78, v24
	v_fma_f32 v139, v185, s79, v24
	v_fma_f32 v136, v158, s80, v24
	v_fma_f32 v137, v159, s81, v24
	v_fma_f32 v134, v156, s82, v24
	v_fma_f32 v135, v157, s83, v24
	s_waitcnt lgkmcnt(0)
	v_mfma_f32_32x32x16_bf16 v[2:17], v[20:23], v[164:167], v[2:17]
	ds_read_b128 v[20:23], v26
	v_fma_f32 v132, v154, s84, v24
	v_fma_f32 v133, v155, s85, v24
	v_fma_f32 v130, v152, s86, v24
	v_fma_f32 v131, v153, s87, v24
	v_fma_f32 v128, v150, s88, v24
	v_fma_f32 v129, v151, s89, v24
	s_waitcnt lgkmcnt(0)
	v_mfma_f32_32x32x16_bf16 v[2:17], v[20:23], v[168:171], v[2:17]
	ds_read_b128 v[20:23], v27
	s_waitcnt lgkmcnt(0)
	v_mfma_f32_32x32x16_bf16 v[2:17], v[20:23], v[172:175], v[2:17]
	ds_read_b128 v[20:23], v19 offset:4096
	s_waitcnt lgkmcnt(0)
	v_mfma_f32_32x32x16_bf16 v[128:143], v[20:23], v[160:163], v[128:143]
	ds_read_b128 v[20:23], v25 offset:4096
	s_waitcnt lgkmcnt(0)
	v_mfma_f32_32x32x16_bf16 v[128:143], v[20:23], v[164:167], v[128:143]
	ds_read_b128 v[20:23], v26 offset:4096
	s_waitcnt lgkmcnt(0)
	v_mfma_f32_32x32x16_bf16 v[128:143], v[20:23], v[168:171], v[128:143]
	ds_read_b128 v[20:23], v27 offset:4096
	s_waitcnt lgkmcnt(0)
	v_mfma_f32_32x32x16_bf16 v[128:143], v[20:23], v[172:175], v[128:143]

; #define MFMA(a, b, c) __builtin_amdgcn_mfma_f32_32x32x16_bf16((a), (b), (c), 0, 0, 0)
; DI void qk_acc(f32x16 (&st)[2], const bf16x8 (&qf)[4], const char* sb, const int (&foff)[4]) {
; #pragma unroll
;   for (int kb = 0; kb < 2; ++kb)
; #pragma unroll
;     for (int ks = 0; ks < 4; ++ks) {
;       const bf16x8 kf = *(const bf16x8*)(sb + kb * 4096 + foff[ks]);
;       st[kb] = MFMA(kf, qf[ks], st[kb]);
;     }
; }
; template <int DV, bool SEL, bool TERM> ...
;     ...
;     const int dmax = wq_max - kp_mul * k0, dmin = wq_min - kp_mul * (k0 + 63);
;     const bool relevant = !(dmax < 0 || dmin >= W) && !(TERM && done);
;     const float dbase = (float)(tqp - kp_mul * (k0 + 4 * h));
;     f32x16 st[2];
;     if (relevant) {
;       const float tb = -slope2 * dbase - mref;
; #pragma unroll
;       for (int kb = 0; kb < 2; ++kb)
; #pragma unroll
;         for (int i = 0; i < 16; ++i) st[kb][i] = __builtin_fmaf(sk, (float)(kb * 32 + (i & 3) + 8 * (i >> 2)), tb);
;       qk_acc(st, qf, sb, foff);
.LBB0_1489:
	s_mul_hi_u32 s0, s17, 0xaaaaaaab
	s_lshr_b32 s1, s0, 1
	s_lshl_b32 s0, s10, 6
	v_or_b32_e32 v0, s0, v172
	s_or_b32 s6, s0, 63
	v_sub_u32_e32 v2, v134, v0
	v_subrev_u32_e32 v3, s0, v157
	v_subrev_u32_e32 v4, s6, v156
	s_brev_b32 s6, 4
	v_cvt_f32_i32_e32 v0, v2
	v_cmp_lt_i32_e32 vcc, -1, v3
	v_cmp_gt_i32_e64 s[6:7], s6, v4
	s_and_b64 s[6:7], vcc, s[6:7]
	v_cmp_eq_u32_e32 vcc, 0, v184
	s_mul_i32 s1, s1, 0xfffee000
	s_and_b64 s[6:7], s[6:7], vcc
	s_and_saveexec_b64 s[10:11], s[6:7]
	s_cbranch_execz .LBB0_1491
	s_add_i32 s18, s93, s1
	v_add_u32_e32 v5, s18, v180
	ds_read_b128 v[8:11], v5
	v_fma_f32 v12, -v136, v0, -v183
	v_fma_f32 v80, 0, v136, v12
	v_add_f32_e32 v81, v136, v12
	v_fma_f32 v82, v144, s26, v12
	v_fma_f32 v83, v145, s27, v12
	v_fma_f32 v84, v144, s28, v12
	v_fma_f32 v85, v145, s29, v12
	v_fma_f32 v86, v144, s30, v12
	v_fma_f32 v87, v145, s31, v12
	v_fma_f32 v88, v144, s34, v12
	v_fma_f32 v89, v145, s35, v12
	v_fma_f32 v90, v144, s36, v12
	v_fma_f32 v91, v145, s37, v12
	v_fma_f32 v92, v144, s38, v12
	v_fma_f32 v93, v145, s39, v12
	v_fma_f32 v94, v144, s40, v12
	v_fma_f32 v95, v145, s41, v12
	v_add_u32_e32 v7, s18, v182
	v_add_u32_e32 v13, s18, v181
	s_waitcnt lgkmcnt(0)
	v_mfma_f32_32x32x16_bf16 v[80:95], v[8:11], v[112:115], v[80:95]
	ds_read_b128 v[8:11], v7
	v_add_u32_e32 v14, s18, v179
	v_mov_b32_e32 v137, v136
	v_fma_f32 v110, v136, s42, v12
	v_fma_f32 v111, v137, s43, v12
	v_fma_f32 v108, v136, s44, v12
	v_fma_f32 v109, v137, s45, v12
	v_fma_f32 v106, v136, s46, v12
	v_fma_f32 v107, v137, s47, v12
	v_fma_f32 v104, v136, s48, v12
	v_fma_f32 v105, v137, s49, v12
	s_waitcnt lgkmcnt(0)
	v_mfma_f32_32x32x16_bf16 v[80:95], v[8:11], v[116:119], v[80:95]
	ds_read_b128 v[8:11], v13
	v_fma_f32 v102, v136, s50, v12
	v_fma_f32 v103, v137, s51, v12
	v_fma_f32 v100, v136, s52, v12
	v_fma_f32 v101, v137, s53, v12
	v_fma_f32 v98, v136, s54, v12
	v_fma_f32 v99, v137, s55, v12
	v_fma_f32 v96, v146, s58, v12
	v_fma_f32 v97, v147, s59, v12
	s_waitcnt lgkmcnt(0)
	v_mfma_f32_32x32x16_bf16 v[80:95], v[8:11], v[120:123], v[80:95]
	ds_read_b128 v[8:11], v14
	s_waitcnt lgkmcnt(0)
	v_mfma_f32_32x32x16_bf16 v[80:95], v[8:11], v[124:127], v[80:95]
	ds_read_b128 v[8:11], v5 offset:4096
	s_waitcnt lgkmcnt(0)
	v_mfma_f32_32x32x16_bf16 v[96:111], v[8:11], v[112:115], v[96:111]
	ds_read_b128 v[8:11], v7 offset:4096
	s_waitcnt lgkmcnt(0)
	v_mfma_f32_32x32x16_bf16 v[96:111], v[8:11], v[116:119], v[96:111]
	ds_read_b128 v[8:11], v13 offset:4096
	s_waitcnt lgkmcnt(0)
	v_mfma_f32_32x32x16_bf16 v[96:111], v[8:11], v[120:123], v[96:111]
	ds_read_b128 v[8:11], v14 offset:4096
	s_waitcnt lgkmcnt(0)
	v_mfma_f32_32x32x16_bf16 v[96:111], v[8:11], v[124:127], v[96:111]

; DI float bflo(unsigned v) { return __uint_as_float(v << 16); }
; DI float bfhi(unsigned v) { return __uint_as_float(v & 0xffff0000u); }
; DI void diff_attn_phase(const Params& p, char* smem) {
;     ...
;     float ss = 0.f;
; #pragma unroll
;     for (int dc = 0; dc < 4; ++dc)
; #pragma unroll
;       for (int g4 = 0; g4 < 4; ++g4) {
;         const u32x2 o1 = *(const volatile u32x2*)(obase + 32 * dc + 8 * g4);
;         const float a0 = ot[dc][4 * g4] * rl - lam * bflo(o1.x);
;         const float a1 = ot[dc][4 * g4 + 1] * rl - lam * bfhi(o1.x);
;         const float a2 = ot[dc][4 * g4 + 2] * rl - lam * bflo(o1.y);
;         const float a3 = ot[dc][4 * g4 + 3] * rl - lam * bfhi(o1.y);
;         ot[dc][4 * g4] = a0; ot[dc][4 * g4 + 1] = a1; ot[dc][4 * g4 + 2] = a2; ot[dc][4 * g4 + 3] = a3;
;         ss += a0 * a0 + a1 * a1 + a2 * a2 + a3 * a3;
;       }
.LBB0_1512:
	s_or_b64 exec, exec, s[0:1]
	s_waitcnt vmcnt(0) lgkmcnt(0)
	s_barrier
	flat_load_dwordx2 v[94:95], v[8:9] sc0 sc1
	s_waitcnt vmcnt(0)
	flat_load_dwordx2 v[98:99], v[8:9] offset:16 sc0 sc1
	s_waitcnt vmcnt(0)
	flat_load_dwordx2 v[100:101], v[8:9] offset:32 sc0 sc1
	s_waitcnt vmcnt(0)
	flat_load_dwordx2 v[102:103], v[8:9] offset:48 sc0 sc1
	s_waitcnt vmcnt(0)
	flat_load_dwordx2 v[104:105], v[8:9] offset:64 sc0 sc1
	s_waitcnt vmcnt(0)
	flat_load_dwordx2 v[106:107], v[8:9] offset:80 sc0 sc1
	s_waitcnt vmcnt(0)
	flat_load_dwordx2 v[108:109], v[8:9] offset:96 sc0 sc1
	s_waitcnt vmcnt(0)
	flat_load_dwordx2 v[96:97], v[8:9] offset:112 sc0 sc1
	s_waitcnt vmcnt(0)
	flat_load_dwordx2 v[92:93], v[8:9] offset:128 sc0 sc1
	s_waitcnt vmcnt(0)
	flat_load_dwordx2 v[90:91], v[8:9] offset:144 sc0 sc1
	s_waitcnt vmcnt(0)
	flat_load_dwordx2 v[84:85], v[8:9] offset:160 sc0 sc1
	s_waitcnt vmcnt(0)
	flat_load_dwordx2 v[88:89], v[8:9] offset:176 sc0 sc1
	s_waitcnt vmcnt(0)
	flat_load_dwordx2 v[80:81], v[8:9] offset:192 sc0 sc1
	s_waitcnt vmcnt(0)
	flat_load_dwordx2 v[82:83], v[8:9] offset:208 sc0 sc1
	s_waitcnt vmcnt(0)
	flat_load_dwordx2 v[14:15], v[8:9] offset:224 sc0 sc1
	s_waitcnt vmcnt(0)
	flat_load_dwordx2 v[86:87], v[8:9] offset:240 sc0 sc1
	s_waitcnt vmcnt(0)
	v_lshlrev_b32_e32 v2, 2, v155
	v_lshlrev_b32_e32 v7, 2, v2
	v_lshl_add_u64 v[4:5], v[130:131], 0, s[2:3]
	v_lshlrev_b32_e32 v0, 1, v2
	v_lshl_add_u64 v[10:11], v[4:5], 0, v[0:1]
	s_movk_i32 s0, 0x1000
	v_add_co_u32_e32 v4, vcc, s0, v10
	s_mov_b64 s[0:1], 0x1800
	s_nop 0
	v_addc_co_u32_e32 v5, vcc, 0, v11, vcc
	global_load_dwordx2 v[12:13], v[4:5], off offset:2048
	v_lshl_add_u64 v[10:11], v[10:11], 0, s[0:1]
	global_load_dwordx4 v[2:5], v7, s[14:15]
	s_mov_b32 s0, 0x800000
	v_lshlrev_b32_e32 v112, 16, v94
	v_and_b32_e32 v113, 0xffff0000, v94
	s_waitcnt lgkmcnt(0)
	v_lshlrev_b32_e32 v114, 16, v98
	v_and_b32_e32 v115, 0xffff0000, v98
	v_lshlrev_b32_e32 v110, 16, v95
	v_and_b32_e32 v111, 0xffff0000, v95
	v_lshlrev_b32_e32 v94, 16, v99
	v_and_b32_e32 v95, 0xffff0000, v99
	v_lshlrev_b32_e32 v98, 16, v101
	v_and_b32_e32 v99, 0xffff0000, v101
	v_lshlrev_b32_e32 v116, 16, v100
	v_and_b32_e32 v117, 0xffff0000, v100
	v_lshlrev_b32_e32 v100, 16, v103
	v_and_b32_e32 v101, 0xffff0000, v103
	v_pk_mul_f32 v[112:113], v[128:129], v[112:113]
	v_pk_mul_f32 v[114:115], v[128:129], v[114:115]
	v_lshlrev_b32_e32 v118, 16, v102
	v_and_b32_e32 v119, 0xffff0000, v102
	v_pk_mul_f32 v[100:101], v[128:129], v[100:101]
	v_pk_fma_f32 v[142:143], v[64:65], v[6:7], v[112:113] op_sel_hi:[1,0,1] neg_lo:[0,0,1] neg_hi:[0,0,1]
	v_pk_fma_f32 v[138:139], v[68:69], v[6:7], v[114:115] op_sel_hi:[1,0,1] neg_lo:[0,0,1] neg_hi:[0,0,1]
	v_lshlrev_b32_e32 v102, 16, v105
	v_and_b32_e32 v103, 0xffff0000, v105
	v_pk_mul_f32 v[110:111], v[128:129], v[110:111]
	v_pk_mul_f32 v[94:95], v[128:129], v[94:95]
	v_pk_mul_f32 v[120:121], v[128:129], v[118:119]
	v_pk_fma_f32 v[118:119], v[78:79], v[6:7], v[100:101] op_sel_hi:[1,0,1] neg_lo:[0,0,1] neg_hi:[0,0,1]
	v_mul_f32_e32 v0, v143, v143
	v_mul_f32_e32 v100, v139, v139
	v_pk_mul_f32 v[98:99], v[128:129], v[98:99]
	v_pk_mul_f32 v[102:103], v[128:129], v[102:103]
	v_pk_fma_f32 v[140:141], v[66:67], v[6:7], v[110:111] op_sel_hi:[1,0,1] neg_lo:[0,0,1] neg_hi:[0,0,1]
	v_pk_fma_f32 v[136:137], v[70:71], v[6:7], v[94:95] op_sel_hi:[1,0,1] neg_lo:[0,0,1] neg_hi:[0,0,1]
	v_pk_fma_f32 v[124:125], v[76:77], v[6:7], v[120:121] op_sel_hi:[1,0,1] neg_lo:[0,0,1] neg_hi:[0,0,1]
	v_fma_f32 v120, v142, v142, v0
	v_fma_f32 v121, v143, v143, v0
	v_pk_fma_f32 v[100:101], v[138:139], v[138:139], v[100:101] op_sel_hi:[1,1,0]
	v_pk_fma_f32 v[132:133], v[74:75], v[6:7], v[98:99] op_sel_hi:[1,0,1] neg_lo:[0,0,1] neg_hi:[0,0,1]
	v_pk_fma_f32 v[94:95], v[50:51], v[6:7], v[102:103] op_sel_hi:[1,0,1] neg_lo:[0,0,1] neg_hi:[0,0,1]
	v_mul_f32_e32 v98, v141, v141
	v_mul_f32_e32 v102, v137, v137
	v_pk_fma_f32 v[120:121], v[140:141], v[140:141], v[120:121]
	v_pk_fma_f32 v[100:101], v[136:137], v[136:137], v[100:101]
	v_pk_mul_f32 v[116:117], v[128:129], v[116:117]
	v_pk_add_f32 v[98:99], v[98:99], v[120:121] op_sel_hi:[0,1]
	v_pk_add_f32 v[100:101], v[102:103], v[100:101] op_sel_hi:[0,1]
	v_pk_fma_f32 v[134:135], v[72:73], v[6:7], v[116:117] op_sel_hi:[1,0,1] neg_lo:[0,0,1] neg_hi:[0,0,1]
	v_pk_add_f32 v[98:99], v[98:99], v[100:101]
	v_lshlrev_b32_e32 v100, 16, v104
	v_and_b32_e32 v101, 0xffff0000, v104
	v_mul_f32_e32 v110, v135, v135
	v_pk_mul_f32 v[100:101], v[128:129], v[100:101]
	v_mul_f32_e32 v114, v125, v125
	v_pk_fma_f32 v[110:111], v[134:135], v[134:135], v[110:111] op_sel_hi:[1,1,0]
	v_pk_fma_f32 v[130:131], v[48:49], v[6:7], v[100:101] op_sel_hi:[1,0,1] neg_lo:[0,0,1] neg_hi:[0,0,1]
	v_mul_f32_e32 v112, v133, v133
	v_pk_fma_f32 v[114:115], v[124:125], v[124:125], v[114:115] op_sel_hi:[1,1,0]
	v_pk_fma_f32 v[110:111], v[132:133], v[132:133], v[110:111]
	v_mul_f32_e32 v0, v131, v131
	v_mul_f32_e32 v116, v119, v119
	v_pk_fma_f32 v[114:115], v[118:119], v[118:119], v[114:115]
	v_pk_add_f32 v[102:103], v[112:113], v[110:111] op_sel_hi:[0,1]
	v_fma_f32 v100, v130, v130, v0
	v_fma_f32 v101, v131, v131, v0
	v_pk_add_f32 v[110:111], v[116:117], v[114:115] op_sel_hi:[0,1]
	v_pk_add_f32 v[98:99], v[98:99], v[102:103]
	v_pk_fma_f32 v[100:101], v[94:95], v[94:95], v[100:101]
	v_mul_f32_e32 v0, v95, v95
	v_pk_add_f32 v[98:99], v[98:99], v[110:111]
	v_pk_add_f32 v[100:101], v[0:1], v[100:101] op_sel_hi:[0,1]
	v_pk_add_f32 v[98:99], v[98:99], v[100:101]
	v_lshlrev_b32_e32 v100, 16, v107
	v_and_b32_e32 v101, 0xffff0000, v107
	v_pk_mul_f32 v[100:101], v[128:129], v[100:101]
	s_waitcnt vmcnt(1)
; DI float bflo(unsigned v) { return __uint_as_float(v << 16); }
; DI float bfhi(unsigned v) { return __uint_as_float(v & 0xffff0000u); }
; DI void diff_attn_phase(const Params& p, char* smem) {
;     ...
;     float ss = 0.f;
; #pragma unroll
;     for (int dc = 0; dc < 4; ++dc)
; #pragma unroll
;       for (int g4 = 0; g4 < 4; ++g4) {
;         const u32x2 o1 = *(const volatile u32x2*)(obase + 32 * dc + 8 * g4);
;         const float a0 = ot[dc][4 * g4] * rl - lam * bflo(o1.x);
;         const float a1 = ot[dc][4 * g4 + 1] * rl - lam * bfhi(o1.x);
;         const float a2 = ot[dc][4 * g4 + 2] * rl - lam * bflo(o1.y);
;         const float a3 = ot[dc][4 * g4 + 3] * rl - lam * bfhi(o1.y);
;         ot[dc][4 * g4] = a0; ot[dc][4 * g4 + 1] = a1; ot[dc][4 * g4 + 2] = a2; ot[dc][4 * g4 + 3] = a3;
;         ss += a0 * a0 + a1 * a1 + a2 * a2 + a3 * a3;
;       }
	v_lshlrev_b32_e32 v144, 16, v12
	v_pk_fma_f32 v[114:115], v[54:55], v[6:7], v[100:101] op_sel_hi:[1,0,1] neg_lo:[0,0,1] neg_hi:[0,0,1]
	v_lshlrev_b32_e32 v100, 16, v106
	v_and_b32_e32 v101, 0xffff0000, v106
	v_pk_mul_f32 v[100:101], v[128:129], v[100:101]
	s_nop 0
	v_pk_fma_f32 v[126:127], v[52:53], v[6:7], v[100:101] op_sel_hi:[1,0,1] neg_lo:[0,0,1] neg_hi:[0,0,1]
	s_nop 0
	v_mul_f32_e32 v0, v127, v127
	v_fma_f32 v100, v126, v126, v0
	v_fma_f32 v101, v127, v127, v0
	v_mul_f32_e32 v0, v115, v115
	v_pk_fma_f32 v[100:101], v[114:115], v[114:115], v[100:101]
	s_nop 0
	v_pk_add_f32 v[100:101], v[0:1], v[100:101] op_sel_hi:[0,1]
	v_pk_add_f32 v[98:99], v[98:99], v[100:101]
	v_lshlrev_b32_e32 v100, 16, v109
	v_and_b32_e32 v101, 0xffff0000, v109
	v_pk_mul_f32 v[100:101], v[128:129], v[100:101]
	s_nop 0
	v_pk_fma_f32 v[110:111], v[58:59], v[6:7], v[100:101] op_sel_hi:[1,0,1] neg_lo:[0,0,1] neg_hi:[0,0,1]
	v_lshlrev_b32_e32 v100, 16, v108
	v_and_b32_e32 v101, 0xffff0000, v108
	v_pk_mul_f32 v[100:101], v[128:129], v[100:101]
	s_nop 0
	v_pk_fma_f32 v[122:123], v[56:57], v[6:7], v[100:101] op_sel_hi:[1,0,1] neg_lo:[0,0,1] neg_hi:[0,0,1]
	s_nop 0
	v_mul_f32_e32 v0, v123, v123
	v_fma_f32 v100, v122, v122, v0
	v_fma_f32 v101, v123, v123, v0
	v_mul_f32_e32 v0, v111, v111
	v_pk_fma_f32 v[100:101], v[110:111], v[110:111], v[100:101]
	s_nop 0
	v_pk_add_f32 v[100:101], v[0:1], v[100:101] op_sel_hi:[0,1]
	v_pk_add_f32 v[98:99], v[98:99], v[100:101]
	v_lshlrev_b32_e32 v100, 16, v97
	v_and_b32_e32 v101, 0xffff0000, v97
	v_pk_mul_f32 v[100:101], v[128:129], v[100:101]
	s_nop 0
	v_pk_fma_f32 v[106:107], v[62:63], v[6:7], v[100:101] op_sel_hi:[1,0,1] neg_lo:[0,0,1] neg_hi:[0,0,1]
	v_lshlrev_b32_e32 v100, 16, v96
	v_and_b32_e32 v101, 0xffff0000, v96
	v_pk_mul_f32 v[96:97], v[128:129], v[100:101]
	s_nop 0
	v_pk_fma_f32 v[120:121], v[60:61], v[6:7], v[96:97] op_sel_hi:[1,0,1] neg_lo:[0,0,1] neg_hi:[0,0,1]
	s_nop 0
	v_mul_f32_e32 v0, v121, v121
	v_fma_f32 v96, v120, v120, v0
	v_fma_f32 v97, v121, v121, v0
	v_mul_f32_e32 v0, v107, v107
	v_pk_fma_f32 v[96:97], v[106:107], v[106:107], v[96:97]
	s_nop 0
	v_pk_add_f32 v[96:97], v[0:1], v[96:97] op_sel_hi:[0,1]
	v_pk_add_f32 v[96:97], v[98:99], v[96:97]
	v_lshlrev_b32_e32 v98, 16, v93
	v_and_b32_e32 v99, 0xffff0000, v93
	v_pk_mul_f32 v[98:99], v[128:129], v[98:99]
	s_nop 0
	v_pk_fma_f32 v[104:105], v[34:35], v[6:7], v[98:99] op_sel_hi:[1,0,1] neg_lo:[0,0,1] neg_hi:[0,0,1]
	v_lshlrev_b32_e32 v98, 16, v92
	v_and_b32_e32 v99, 0xffff0000, v92
	v_pk_mul_f32 v[92:93], v[128:129], v[98:99]
	s_nop 0
	v_pk_fma_f32 v[116:117], v[32:33], v[6:7], v[92:93] op_sel_hi:[1,0,1] neg_lo:[0,0,1] neg_hi:[0,0,1]
	s_nop 0
	v_mul_f32_e32 v0, v117, v117
	v_fma_f32 v92, v116, v116, v0
	v_fma_f32 v93, v117, v117, v0
	v_mul_f32_e32 v0, v105, v105
	v_pk_fma_f32 v[92:93], v[104:105], v[104:105], v[92:93]
	s_nop 0
	v_pk_add_f32 v[92:93], v[0:1], v[92:93] op_sel_hi:[0,1]
	v_pk_add_f32 v[92:93], v[96:97], v[92:93]
	v_lshlrev_b32_e32 v96, 16, v91
	v_and_b32_e32 v97, 0xffff0000, v91
	v_pk_mul_f32 v[96:97], v[128:129], v[96:97]
	s_nop 0
	v_pk_fma_f32 v[98:99], v[38:39], v[6:7], v[96:97] op_sel_hi:[1,0,1] neg_lo:[0,0,1] neg_hi:[0,0,1]
	v_lshlrev_b32_e32 v96, 16, v90
	v_and_b32_e32 v97, 0xffff0000, v90
	v_pk_mul_f32 v[90:91], v[128:129], v[96:97]
	v_lshlrev_b32_e32 v96, 16, v84
	v_pk_fma_f32 v[112:113], v[36:37], v[6:7], v[90:91] op_sel_hi:[1,0,1] neg_lo:[0,0,1] neg_hi:[0,0,1]
	v_and_b32_e32 v97, 0xffff0000, v84
	v_mul_f32_e32 v0, v113, v113
	v_fma_f32 v90, v112, v112, v0
	v_fma_f32 v91, v113, v113, v0
	v_mul_f32_e32 v0, v99, v99
	v_pk_fma_f32 v[90:91], v[98:99], v[98:99], v[90:91]
	s_nop 0
	v_pk_add_f32 v[90:91], v[0:1], v[90:91] op_sel_hi:[0,1]
	v_pk_add_f32 v[90:91], v[92:93], v[90:91]
	v_lshlrev_b32_e32 v92, 16, v85
	v_and_b32_e32 v93, 0xffff0000, v85
	v_pk_mul_f32 v[84:85], v[128:129], v[96:97]
	v_lshlrev_b32_e32 v96, 16, v88
	v_and_b32_e32 v97, 0xffff0000, v88
	v_pk_fma_f32 v[108:109], v[40:41], v[6:7], v[84:85] op_sel_hi:[1,0,1] neg_lo:[0,0,1] neg_hi:[0,0,1]
	v_lshlrev_b32_e32 v84, 16, v89
	v_and_b32_e32 v85, 0xffff0000, v89
	v_pk_mul_f32 v[88:89], v[128:129], v[96:97]
	v_pk_mul_f32 v[92:93], v[128:129], v[92:93]
	v_pk_fma_f32 v[100:101], v[44:45], v[6:7], v[88:89] op_sel_hi:[1,0,1] neg_lo:[0,0,1] neg_hi:[0,0,1]
	v_pk_mul_f32 v[84:85], v[128:129], v[84:85]
	v_mov_b32_e32 v146, v109
	v_mov_b32_e32 v147, v101
	v_pk_fma_f32 v[92:93], v[42:43], v[6:7], v[92:93] op_sel_hi:[1,0,1] neg_lo:[0,0,1] neg_hi:[0,0,1]
	v_pk_fma_f32 v[84:85], v[46:47], v[6:7], v[84:85] op_sel_hi:[1,0,1] neg_lo:[0,0,1] neg_hi:[0,0,1]
	v_mov_b32_e32 v102, v108
	v_mov_b32_e32 v103, v100
	v_pk_mul_f32 v[146:147], v[146:147], v[146:147]
	v_mov_b32_e32 v88, v92
	v_mov_b32_e32 v89, v84
	v_pk_fma_f32 v[102:103], v[102:103], v[102:103], v[146:147]
	v_mov_b32_e32 v96, v93
	v_mov_b32_e32 v97, v85
	v_pk_fma_f32 v[88:89], v[88:89], v[88:89], v[102:103]
	s_nop 0
	v_pk_fma_f32 v[88:89], v[96:97], v[96:97], v[88:89]
	s_nop 0
	v_pk_add_f32 v[90:91], v[90:91], v[88:89]
	s_nop 0
	v_pk_add_f32 v[96:97], v[90:91], v[88:89] op_sel:[0,1] op_sel_hi:[1,0]
	v_lshlrev_b32_e32 v90, 16, v80
	v_and_b32_e32 v91, 0xffff0000, v80
	v_lshlrev_b32_e32 v88, 16, v81
	v_and_b32_e32 v89, 0xffff0000, v81
	v_pk_mul_f32 v[80:81], v[128:129], v[90:91]
	v_lshlrev_b32_e32 v90, 16, v82
	v_and_b32_e32 v91, 0xffff0000, v82
	v_pk_fma_f32 v[102:103], v[16:17], v[6:7], v[80:81] op_sel_hi:[1,0,1] neg_lo:[0,0,1] neg_hi:[0,0,1]
	v_lshlrev_b32_e32 v80, 16, v83
	v_and_b32_e32 v81, 0xffff0000, v83
	v_pk_mul_f32 v[82:83], v[128:129], v[90:91]
	v_pk_mul_f32 v[88:89], v[128:129], v[88:89]
	v_pk_fma_f32 v[90:91], v[20:21], v[6:7], v[82:83] op_sel_hi:[1,0,1] neg_lo:[0,0,1] neg_hi:[0,0,1]
; DI unsigned pack2(float a, float b) { v2f f = {a, b}; return __builtin_bit_cast(unsigned, __builtin_convertvector(f, v2bf)); }
; DI float bflo(unsigned v) { return __uint_as_float(v << 16); }
; DI float bfhi(unsigned v) { return __uint_as_float(v & 0xffff0000u); }
; DI float xsumh(float v) { const u32x2 r = __builtin_amdgcn_permlane32_swap(__float_as_uint(v), __float_as_uint(v), false, false); return __uint_as_float(r[0]) + __uint_as_float(r[1]); }
; DI void diff_attn_phase(const Params& p, char* smem) {
;     ...
;     ss = xsumh(ss);
;     const float ri = rsqrtf(ss * (1.f / 128.f) + RMS_EPS) * (1.f - lambda_init);
; #pragma unroll
;     for (int dc = 0; dc < 4; ++dc)
; #pragma unroll
;       for (int g4 = 0; g4 < 4; ++g4) {
;         const int dv = 32 * dc + 8 * g4 + 4 * h;
;         const float4 sg = *(const float4*)(p.b_sub_gain + dv);
;         const u32x2 zz = *(const u32x2*)(p.qkvz + tok * LD + 3072 + hd * 128 + dv);
;         u32x2 o;
;         o.x = pack2(ot[dc][4 * g4] * ri * sg.x * bflo(zz.x), ot[dc][4 * g4 + 1] * ri * sg.y * bfhi(zz.x));
;         o.y = pack2(ot[dc][4 * g4 + 2] * ri * sg.z * bflo(zz.y), ot[dc][4 * g4 + 3] * ri * sg.w * bfhi(zz.y));
;         *(u32x2*)(p.u + tok * 1024 + hd * 128 + dv) = o;
;       }
	v_pk_mul_f32 v[80:81], v[128:129], v[80:81]
	v_mov_b32_e32 v158, v103
	v_mov_b32_e32 v159, v91
	v_pk_fma_f32 v[88:89], v[18:19], v[6:7], v[88:89] op_sel_hi:[1,0,1] neg_lo:[0,0,1] neg_hi:[0,0,1]
	v_pk_fma_f32 v[80:81], v[22:23], v[6:7], v[80:81] op_sel_hi:[1,0,1] neg_lo:[0,0,1] neg_hi:[0,0,1]
	v_mov_b32_e32 v156, v102
	v_mov_b32_e32 v157, v90
	v_pk_mul_f32 v[158:159], v[158:159], v[158:159]
	v_mov_b32_e32 v82, v88
	v_mov_b32_e32 v83, v80
	v_pk_fma_f32 v[156:157], v[156:157], v[156:157], v[158:159]
	v_mov_b32_e32 v146, v89
	v_mov_b32_e32 v147, v81
	v_pk_fma_f32 v[82:83], v[82:83], v[82:83], v[156:157]
	v_lshlrev_b32_e32 v156, 16, v86
	v_pk_fma_f32 v[82:83], v[146:147], v[146:147], v[82:83]
	v_and_b32_e32 v157, 0xffff0000, v86
	v_pk_add_f32 v[96:97], v[96:97], v[82:83]
	s_nop 0
	v_pk_add_f32 v[146:147], v[96:97], v[82:83] op_sel:[0,1] op_sel_hi:[1,0]
	v_lshlrev_b32_e32 v96, 16, v14
	v_and_b32_e32 v97, 0xffff0000, v14
	v_lshlrev_b32_e32 v82, 16, v15
	v_and_b32_e32 v83, 0xffff0000, v15
	v_pk_mul_f32 v[14:15], v[128:129], v[96:97]
	v_pk_mul_f32 v[82:83], v[128:129], v[82:83]
	v_pk_fma_f32 v[96:97], v[24:25], v[6:7], v[14:15] op_sel_hi:[1,0,1] neg_lo:[0,0,1] neg_hi:[0,0,1]
	v_lshlrev_b32_e32 v14, 16, v87
	v_and_b32_e32 v15, 0xffff0000, v87
	v_pk_mul_f32 v[86:87], v[128:129], v[156:157]
	v_pk_mul_f32 v[14:15], v[128:129], v[14:15]
	v_pk_fma_f32 v[86:87], v[28:29], v[6:7], v[86:87] op_sel_hi:[1,0,1] neg_lo:[0,0,1] neg_hi:[0,0,1]
	v_mov_b32_e32 v162, v97
	v_mov_b32_e32 v163, v87
	v_pk_fma_f32 v[82:83], v[26:27], v[6:7], v[82:83] op_sel_hi:[1,0,1] neg_lo:[0,0,1] neg_hi:[0,0,1]
	v_pk_fma_f32 v[14:15], v[30:31], v[6:7], v[14:15] op_sel_hi:[1,0,1] neg_lo:[0,0,1] neg_hi:[0,0,1]
	v_mov_b32_e32 v160, v96
	v_mov_b32_e32 v161, v86
	v_pk_mul_f32 v[162:163], v[162:163], v[162:163]
	v_mov_b32_e32 v156, v82
	v_mov_b32_e32 v157, v14
	v_pk_fma_f32 v[160:161], v[160:161], v[160:161], v[162:163]
	v_mov_b32_e32 v158, v83
	v_mov_b32_e32 v159, v15
	v_pk_fma_f32 v[156:157], v[156:157], v[156:157], v[160:161]
	s_nop 0
	v_pk_fma_f32 v[156:157], v[158:159], v[158:159], v[156:157]
	s_nop 0
	v_pk_add_f32 v[146:147], v[146:147], v[156:157]
	s_nop 0
	v_pk_add_f32 v[146:147], v[146:147], v[156:157] op_sel:[0,1] op_sel_hi:[1,0]
	s_nop 0
	v_mov_b32_e32 v0, v146
	s_nop 1
	v_permlane32_swap_b32_e32 v146, v0
	v_add_f32_e32 v0, v146, v0
	v_fmamk_f32 v0, v0, 0x3c000000, v150
	v_mul_f32_e32 v145, 0x4b800000, v0
	v_cmp_gt_f32_e32 vcc, s0, v0
	s_mov_b64 s[0:1], 0
	s_nop 0
	v_cndmask_b32_e32 v0, v0, v145, vcc
	v_rsq_f32_e32 v0, v0
	v_and_b32_e32 v145, 0xffff0000, v12
	v_lshlrev_b32_e32 v12, 16, v13
	v_and_b32_e32 v13, 0xffff0000, v13
	v_mul_f32_e32 v146, 0x45800000, v0
	v_cndmask_b32_e32 v0, v0, v146, vcc
	v_mul_f32_e32 v0, 0x3f24fd5c, v0
	v_pk_mul_f32 v[142:143], v[142:143], v[0:1] op_sel_hi:[1,0]
	v_pk_mul_f32 v[140:141], v[140:141], v[0:1] op_sel_hi:[1,0]
	s_waitcnt vmcnt(0)
	v_pk_mul_f32 v[2:3], v[2:3], v[142:143]
	v_pk_mul_f32 v[4:5], v[4:5], v[140:141]
	v_pk_mul_f32 v[2:3], v[2:3], v[144:145]
	v_pk_mul_f32 v[4:5], v[4:5], v[12:13]
	v_cvt_pk_bf16_f32 v2, v2, v3
	v_cvt_pk_bf16_f32 v3, v4, v5
	global_store_dwordx2 v[8:9], v[2:3], off
	global_load_dwordx4 v[2:5], v7, s[14:15] offset:32
	s_nop 0
	global_load_dwordx2 v[12:13], v[10:11], off offset:16
	v_pk_mul_f32 v[138:139], v[138:139], v[0:1] op_sel_hi:[1,0]
	v_pk_mul_f32 v[136:137], v[136:137], v[0:1] op_sel_hi:[1,0]
	v_pk_mul_f32 v[134:135], v[134:135], v[0:1] op_sel_hi:[1,0]
	v_pk_mul_f32 v[132:133], v[132:133], v[0:1] op_sel_hi:[1,0]
	v_pk_mul_f32 v[124:125], v[124:125], v[0:1] op_sel_hi:[1,0]
	v_pk_mul_f32 v[118:119], v[118:119], v[0:1] op_sel_hi:[1,0]
	v_pk_mul_f32 v[94:95], v[94:95], v[0:1] op_sel_hi:[1,0]
	v_pk_mul_f32 v[114:115], v[114:115], v[0:1] op_sel_hi:[1,0]
	v_pk_mul_f32 v[110:111], v[110:111], v[0:1] op_sel_hi:[1,0]
	v_pk_mul_f32 v[106:107], v[106:107], v[0:1] op_sel_hi:[1,0]
	v_pk_mul_f32 v[104:105], v[104:105], v[0:1] op_sel_hi:[1,0]
	v_pk_mul_f32 v[98:99], v[98:99], v[0:1] op_sel_hi:[1,0]
	v_pk_mul_f32 v[92:93], v[92:93], v[0:1] op_sel_hi:[1,0]
	v_pk_mul_f32 v[84:85], v[84:85], v[0:1] op_sel_hi:[1,0]
	v_pk_mul_f32 v[88:89], v[88:89], v[0:1] op_sel_hi:[1,0]
	v_pk_mul_f32 v[80:81], v[80:81], v[0:1] op_sel_hi:[1,0]
	v_pk_mul_f32 v[82:83], v[82:83], v[0:1] op_sel_hi:[1,0]
	v_pk_mul_f32 v[14:15], v[14:15], v[0:1] op_sel_hi:[1,0]
	s_waitcnt vmcnt(1)
	v_pk_mul_f32 v[2:3], v[2:3], v[138:139]
	s_waitcnt vmcnt(0)
	v_lshlrev_b32_e32 v138, 16, v12
	v_and_b32_e32 v139, 0xffff0000, v12
	v_pk_mul_f32 v[4:5], v[136:137], v[4:5]
	v_lshlrev_b32_e32 v12, 16, v13
	v_and_b32_e32 v13, 0xffff0000, v13
	v_pk_mul_f32 v[2:3], v[2:3], v[138:139]
	v_pk_mul_f32 v[4:5], v[4:5], v[12:13]
	v_cvt_pk_bf16_f32 v2, v2, v3
	v_cvt_pk_bf16_f32 v3, v4, v5
	global_store_dwordx2 v[8:9], v[2:3], off offset:16
	global_load_dwordx4 v[2:5], v7, s[14:15] offset:64
	s_nop 0
	global_load_dwordx2 v[12:13], v[10:11], off offset:32
	s_waitcnt vmcnt(1)
	v_pk_mul_f32 v[2:3], v[134:135], v[2:3]
	s_waitcnt vmcnt(0)
	v_lshlrev_b32_e32 v134, 16, v12
	v_and_b32_e32 v135, 0xffff0000, v12
	v_pk_mul_f32 v[4:5], v[132:133], v[4:5]
	v_lshlrev_b32_e32 v12, 16, v13
	v_and_b32_e32 v13, 0xffff0000, v13
	v_pk_mul_f32 v[2:3], v[2:3], v[134:135]
	v_pk_mul_f32 v[4:5], v[4:5], v[12:13]
	v_cvt_pk_bf16_f32 v2, v2, v3
	v_cvt_pk_bf16_f32 v3, v4, v5
	global_store_dwordx2 v[8:9], v[2:3], off offset:32
	global_load_dwordx4 v[2:5], v7, s[14:15] offset:96
	s_nop 0
	global_load_dwordx2 v[12:13], v[10:11], off offset:48
	s_waitcnt vmcnt(1)
	v_pk_mul_f32 v[2:3], v[124:125], v[2:3]
	s_waitcnt vmcnt(0)
; DI unsigned pack2(float a, float b) { v2f f = {a, b}; return __builtin_bit_cast(unsigned, __builtin_convertvector(f, v2bf)); }
; DI float bflo(unsigned v) { return __uint_as_float(v << 16); }
; DI float bfhi(unsigned v) { return __uint_as_float(v & 0xffff0000u); }
; DI void diff_attn_phase(const Params& p, char* smem) {
;     ...
; #pragma unroll
;     for (int dc = 0; dc < 4; ++dc)
; #pragma unroll
;       for (int g4 = 0; g4 < 4; ++g4) {
;         const int dv = 32 * dc + 8 * g4 + 4 * h;
;         const float4 sg = *(const float4*)(p.b_sub_gain + dv);
;         const u32x2 zz = *(const u32x2*)(p.qkvz + tok * LD + 3072 + hd * 128 + dv);
;         u32x2 o;
;         o.x = pack2(ot[dc][4 * g4] * ri * sg.x * bflo(zz.x), ot[dc][4 * g4 + 1] * ri * sg.y * bfhi(zz.x));
;         o.y = pack2(ot[dc][4 * g4 + 2] * ri * sg.z * bflo(zz.y), ot[dc][4 * g4 + 3] * ri * sg.w * bfhi(zz.y));
;         *(u32x2*)(p.u + tok * 1024 + hd * 128 + dv) = o;
;       }
	v_lshlrev_b32_e32 v124, 16, v12
	v_and_b32_e32 v125, 0xffff0000, v12
	v_pk_mul_f32 v[4:5], v[118:119], v[4:5]
	v_lshlrev_b32_e32 v12, 16, v13
	v_and_b32_e32 v13, 0xffff0000, v13
	v_pk_mul_f32 v[2:3], v[2:3], v[124:125]
	v_pk_mul_f32 v[4:5], v[4:5], v[12:13]
	v_cvt_pk_bf16_f32 v2, v2, v3
	v_cvt_pk_bf16_f32 v3, v4, v5
	global_store_dwordx2 v[8:9], v[2:3], off offset:48
	global_load_dwordx4 v[2:5], v7, s[14:15] offset:128
	s_nop 0
	global_load_dwordx2 v[12:13], v[10:11], off offset:64
	v_pk_mul_f32 v[118:119], v[130:131], v[0:1] op_sel_hi:[1,0]
	s_waitcnt vmcnt(1)
	v_pk_mul_f32 v[4:5], v[94:95], v[4:5]
	v_pk_mul_f32 v[2:3], v[118:119], v[2:3]
	s_waitcnt vmcnt(0)
	v_lshlrev_b32_e32 v118, 16, v12
	v_and_b32_e32 v119, 0xffff0000, v12
	v_lshlrev_b32_e32 v12, 16, v13
	v_and_b32_e32 v13, 0xffff0000, v13
	v_pk_mul_f32 v[2:3], v[2:3], v[118:119]
	v_pk_mul_f32 v[4:5], v[4:5], v[12:13]
	v_cvt_pk_bf16_f32 v2, v2, v3
	v_cvt_pk_bf16_f32 v3, v4, v5
	global_store_dwordx2 v[8:9], v[2:3], off offset:64
	global_load_dwordx4 v[2:5], v7, s[14:15] offset:160
	s_nop 0
	global_load_dwordx2 v[12:13], v[10:11], off offset:80
	v_pk_mul_f32 v[94:95], v[126:127], v[0:1] op_sel_hi:[1,0]
	s_waitcnt vmcnt(1)
	v_pk_mul_f32 v[4:5], v[114:115], v[4:5]
	v_pk_mul_f32 v[2:3], v[94:95], v[2:3]
	s_waitcnt vmcnt(0)
	v_lshlrev_b32_e32 v94, 16, v12
	v_and_b32_e32 v95, 0xffff0000, v12
	v_lshlrev_b32_e32 v12, 16, v13
	v_and_b32_e32 v13, 0xffff0000, v13
	v_pk_mul_f32 v[2:3], v[2:3], v[94:95]
	v_pk_mul_f32 v[4:5], v[4:5], v[12:13]
	v_cvt_pk_bf16_f32 v2, v2, v3
	v_cvt_pk_bf16_f32 v3, v4, v5
	global_store_dwordx2 v[8:9], v[2:3], off offset:80
	global_load_dwordx4 v[2:5], v7, s[14:15] offset:192
	s_nop 0
	global_load_dwordx2 v[12:13], v[10:11], off offset:96
	v_pk_mul_f32 v[94:95], v[122:123], v[0:1] op_sel_hi:[1,0]
	s_waitcnt vmcnt(1)
	v_pk_mul_f32 v[4:5], v[110:111], v[4:5]
	v_pk_mul_f32 v[2:3], v[94:95], v[2:3]
	s_waitcnt vmcnt(0)
	v_lshlrev_b32_e32 v94, 16, v12
	v_and_b32_e32 v95, 0xffff0000, v12
	v_lshlrev_b32_e32 v12, 16, v13
	v_and_b32_e32 v13, 0xffff0000, v13
	v_pk_mul_f32 v[2:3], v[2:3], v[94:95]
	v_pk_mul_f32 v[4:5], v[4:5], v[12:13]
	v_cvt_pk_bf16_f32 v2, v2, v3
	v_cvt_pk_bf16_f32 v3, v4, v5
	global_store_dwordx2 v[8:9], v[2:3], off offset:96
	global_load_dwordx4 v[2:5], v7, s[14:15] offset:224
	s_nop 0
	global_load_dwordx2 v[12:13], v[10:11], off offset:112
	v_pk_mul_f32 v[94:95], v[120:121], v[0:1] op_sel_hi:[1,0]
	s_waitcnt vmcnt(1)
	v_pk_mul_f32 v[4:5], v[106:107], v[4:5]
	v_pk_mul_f32 v[2:3], v[94:95], v[2:3]
	s_waitcnt vmcnt(0)
	v_lshlrev_b32_e32 v94, 16, v12
	v_and_b32_e32 v95, 0xffff0000, v12
	v_lshlrev_b32_e32 v12, 16, v13
	v_and_b32_e32 v13, 0xffff0000, v13
	v_pk_mul_f32 v[2:3], v[2:3], v[94:95]
	v_pk_mul_f32 v[4:5], v[4:5], v[12:13]
	v_cvt_pk_bf16_f32 v2, v2, v3
	v_cvt_pk_bf16_f32 v3, v4, v5
	global_store_dwordx2 v[8:9], v[2:3], off offset:112
	global_load_dwordx4 v[2:5], v7, s[14:15] offset:256
	s_nop 0
	global_load_dwordx2 v[12:13], v[10:11], off offset:128
	v_pk_mul_f32 v[94:95], v[116:117], v[0:1] op_sel_hi:[1,0]
	s_waitcnt vmcnt(1)
	v_pk_mul_f32 v[4:5], v[104:105], v[4:5]
	v_pk_mul_f32 v[2:3], v[94:95], v[2:3]
	s_waitcnt vmcnt(0)
	v_lshlrev_b32_e32 v94, 16, v12
	v_and_b32_e32 v95, 0xffff0000, v12
	v_lshlrev_b32_e32 v12, 16, v13
	v_and_b32_e32 v13, 0xffff0000, v13
	v_pk_mul_f32 v[2:3], v[2:3], v[94:95]
	v_pk_mul_f32 v[4:5], v[4:5], v[12:13]
	v_cvt_pk_bf16_f32 v2, v2, v3
	v_cvt_pk_bf16_f32 v3, v4, v5
	global_store_dwordx2 v[8:9], v[2:3], off offset:128
	global_load_dwordx4 v[2:5], v7, s[14:15] offset:288
	s_nop 0
	global_load_dwordx2 v[12:13], v[10:11], off offset:144
	v_pk_mul_f32 v[94:95], v[112:113], v[0:1] op_sel_hi:[1,0]
	s_waitcnt vmcnt(1)
	v_pk_mul_f32 v[4:5], v[98:99], v[4:5]
	v_pk_mul_f32 v[2:3], v[94:95], v[2:3]
	s_waitcnt vmcnt(0)
; DI unsigned pack2(float a, float b) { v2f f = {a, b}; return __builtin_bit_cast(unsigned, __builtin_convertvector(f, v2bf)); }
; DI float bflo(unsigned v) { return __uint_as_float(v << 16); }
; DI float bfhi(unsigned v) { return __uint_as_float(v & 0xffff0000u); }
; DI void diff_attn_phase(const Params& p, char* smem) {
;     ...
; #pragma unroll
;     for (int dc = 0; dc < 4; ++dc)
; #pragma unroll
;       for (int g4 = 0; g4 < 4; ++g4) {
;         const int dv = 32 * dc + 8 * g4 + 4 * h;
;         const float4 sg = *(const float4*)(p.b_sub_gain + dv);
;         const u32x2 zz = *(const u32x2*)(p.qkvz + tok * LD + 3072 + hd * 128 + dv);
;         u32x2 o;
;         o.x = pack2(ot[dc][4 * g4] * ri * sg.x * bflo(zz.x), ot[dc][4 * g4 + 1] * ri * sg.y * bfhi(zz.x));
;         o.y = pack2(ot[dc][4 * g4 + 2] * ri * sg.z * bflo(zz.y), ot[dc][4 * g4 + 3] * ri * sg.w * bfhi(zz.y));
;         *(u32x2*)(p.u + tok * 1024 + hd * 128 + dv) = o;
;       }
	v_lshlrev_b32_e32 v94, 16, v12
	v_and_b32_e32 v95, 0xffff0000, v12
	v_lshlrev_b32_e32 v12, 16, v13
	v_and_b32_e32 v13, 0xffff0000, v13
	v_pk_mul_f32 v[2:3], v[2:3], v[94:95]
	v_pk_mul_f32 v[4:5], v[4:5], v[12:13]
	v_cvt_pk_bf16_f32 v2, v2, v3
	v_cvt_pk_bf16_f32 v3, v4, v5
	global_store_dwordx2 v[8:9], v[2:3], off offset:144
	global_load_dwordx4 v[2:5], v7, s[14:15] offset:320
	s_nop 0
	global_load_dwordx2 v[12:13], v[10:11], off offset:160
	v_pk_mul_f32 v[94:95], v[108:109], v[0:1] op_sel_hi:[1,0]
	s_waitcnt vmcnt(1)
	v_pk_mul_f32 v[4:5], v[92:93], v[4:5]
	v_pk_mul_f32 v[2:3], v[94:95], v[2:3]
	s_waitcnt vmcnt(0)
	v_lshlrev_b32_e32 v94, 16, v12
	v_and_b32_e32 v95, 0xffff0000, v12
	v_lshlrev_b32_e32 v12, 16, v13
	v_and_b32_e32 v13, 0xffff0000, v13
	v_pk_mul_f32 v[2:3], v[2:3], v[94:95]
	v_pk_mul_f32 v[4:5], v[4:5], v[12:13]
	v_cvt_pk_bf16_f32 v2, v2, v3
	v_cvt_pk_bf16_f32 v3, v4, v5
	global_store_dwordx2 v[8:9], v[2:3], off offset:160
	global_load_dwordx4 v[2:5], v7, s[14:15] offset:352
	s_nop 0
	global_load_dwordx2 v[12:13], v[10:11], off offset:176
	v_pk_mul_f32 v[92:93], v[100:101], v[0:1] op_sel_hi:[1,0]
	s_waitcnt vmcnt(1)
	v_pk_mul_f32 v[4:5], v[84:85], v[4:5]
	v_pk_mul_f32 v[2:3], v[92:93], v[2:3]
	s_waitcnt vmcnt(0)
	v_lshlrev_b32_e32 v92, 16, v12
	v_and_b32_e32 v93, 0xffff0000, v12
	v_lshlrev_b32_e32 v12, 16, v13
	v_and_b32_e32 v13, 0xffff0000, v13
	v_pk_mul_f32 v[2:3], v[2:3], v[92:93]
	v_pk_mul_f32 v[4:5], v[4:5], v[12:13]
	v_cvt_pk_bf16_f32 v2, v2, v3
	v_cvt_pk_bf16_f32 v3, v4, v5
	global_store_dwordx2 v[8:9], v[2:3], off offset:176
	global_load_dwordx4 v[2:5], v7, s[14:15] offset:384
	s_nop 0
	global_load_dwordx2 v[12:13], v[10:11], off offset:192
	v_pk_mul_f32 v[84:85], v[102:103], v[0:1] op_sel_hi:[1,0]
	s_waitcnt vmcnt(1)
	v_pk_mul_f32 v[4:5], v[88:89], v[4:5]
	v_pk_mul_f32 v[2:3], v[84:85], v[2:3]
	s_waitcnt vmcnt(0)
	v_lshlrev_b32_e32 v84, 16, v12
	v_and_b32_e32 v85, 0xffff0000, v12
	v_lshlrev_b32_e32 v12, 16, v13
	v_and_b32_e32 v13, 0xffff0000, v13
	v_pk_mul_f32 v[2:3], v[2:3], v[84:85]
	v_pk_mul_f32 v[4:5], v[4:5], v[12:13]
	v_cvt_pk_bf16_f32 v2, v2, v3
	v_cvt_pk_bf16_f32 v3, v4, v5
	global_store_dwordx2 v[8:9], v[2:3], off offset:192
	global_load_dwordx4 v[2:5], v7, s[14:15] offset:416
	s_nop 0
	global_load_dwordx2 v[12:13], v[10:11], off offset:208
	v_pk_mul_f32 v[84:85], v[90:91], v[0:1] op_sel_hi:[1,0]
	s_waitcnt vmcnt(1)
	v_pk_mul_f32 v[4:5], v[80:81], v[4:5]
	v_pk_mul_f32 v[2:3], v[84:85], v[2:3]
	s_waitcnt vmcnt(0)
	v_lshlrev_b32_e32 v84, 16, v12
	v_and_b32_e32 v85, 0xffff0000, v12
	v_lshlrev_b32_e32 v12, 16, v13
	v_and_b32_e32 v13, 0xffff0000, v13
	v_pk_mul_f32 v[2:3], v[2:3], v[84:85]
	v_pk_mul_f32 v[4:5], v[4:5], v[12:13]
	v_cvt_pk_bf16_f32 v2, v2, v3
	v_cvt_pk_bf16_f32 v3, v4, v5
	global_store_dwordx2 v[8:9], v[2:3], off offset:208
	global_load_dwordx4 v[2:5], v7, s[14:15] offset:448
	s_nop 0
	global_load_dwordx2 v[12:13], v[10:11], off offset:224
	v_pk_mul_f32 v[80:81], v[96:97], v[0:1] op_sel_hi:[1,0]
	s_waitcnt vmcnt(1)
	v_pk_mul_f32 v[4:5], v[82:83], v[4:5]
	v_pk_mul_f32 v[2:3], v[80:81], v[2:3]
	s_waitcnt vmcnt(0)
	v_lshlrev_b32_e32 v80, 16, v12
	v_and_b32_e32 v81, 0xffff0000, v12
	v_lshlrev_b32_e32 v12, 16, v13
	v_and_b32_e32 v13, 0xffff0000, v13
	v_pk_mul_f32 v[2:3], v[2:3], v[80:81]
	v_pk_mul_f32 v[4:5], v[4:5], v[12:13]
	v_cvt_pk_bf16_f32 v2, v2, v3
	v_cvt_pk_bf16_f32 v3, v4, v5
	global_store_dwordx2 v[8:9], v[2:3], off offset:224
	global_load_dwordx4 v[2:5], v7, s[14:15] offset:480
	s_nop 0
	global_load_dwordx2 v[10:11], v[10:11], off offset:240
	v_pk_mul_f32 v[12:13], v[86:87], v[0:1] op_sel_hi:[1,0]
	s_waitcnt vmcnt(1)
	v_pk_mul_f32 v[4:5], v[14:15], v[4:5]
	v_pk_mul_f32 v[2:3], v[12:13], v[2:3]
	s_waitcnt vmcnt(0)
	v_lshlrev_b32_e32 v12, 16, v10
	v_and_b32_e32 v13, 0xffff0000, v10
	v_lshlrev_b32_e32 v10, 16, v11
	v_and_b32_e32 v11, 0xffff0000, v11
	v_pk_mul_f32 v[2:3], v[2:3], v[12:13]
	v_pk_mul_f32 v[4:5], v[4:5], v[10:11]
	v_cvt_pk_bf16_f32 v2, v2, v3
	v_cvt_pk_bf16_f32 v3, v4, v5
	global_store_dwordx2 v[8:9], v[2:3], off offset:240

; #define MFMA(a, b, c) __builtin_amdgcn_mfma_f32_32x32x16_bf16((a), (b), (c), 0, 0, 0)
; DI void qk_acc(f32x16 (&st)[2], const bf16x8 (&qf)[4], const char* sb, const int (&foff)[4]) {
; #pragma unroll
;   for (int kb = 0; kb < 2; ++kb)
; #pragma unroll
;     for (int ks = 0; ks < 4; ++ks) {
;       const bf16x8 kf = *(const bf16x8*)(sb + kb * 4096 + foff[ks]);
;       st[kb] = MFMA(kf, qf[ks], st[kb]);
;     }
; }
; template <int DV, bool SEL, bool TERM> ...
;     ...
;     const int dmax = wq_max - kp_mul * k0, dmin = wq_min - kp_mul * (k0 + 63);
;     const bool relevant = !(dmax < 0 || dmin >= W) && !(TERM && done);
;     const float dbase = (float)(tqp - kp_mul * (k0 + 4 * h));
;     f32x16 st[2];
;     if (relevant) {
;       const float tb = -slope2 * dbase - mref;
; #pragma unroll
;       for (int kb = 0; kb < 2; ++kb)
; #pragma unroll
;         for (int i = 0; i < 16; ++i) st[kb][i] = __builtin_fmaf(sk, (float)(kb * 32 + (i & 3) + 8 * (i >> 2)), tb);
;       qk_acc(st, qf, sb, foff);
.LBB0_2003:
	s_lshl_b32 s1, s86, 6
	v_or_b32_e32 v0, s1, v166
	v_sub_u32_e32 v2, v130, v0
	s_or_b32 s4, s1, 63
	v_cvt_f32_i32_e32 v0, v2
	s_mul_hi_u32 s0, s97, 0xaaaaaaab
	s_waitcnt lgkmcnt(0)
	v_subrev_u32_e32 v3, s1, v152
	v_subrev_u32_e32 v4, s4, v151
	s_lshr_b32 s0, s0, 1
	v_cmp_lt_i32_e32 vcc, -1, v3
	v_cmp_gt_i32_e64 s[4:5], s90, v4
	s_mul_i32 s0, s0, 0xfffee000
	s_and_b64 s[4:5], vcc, s[4:5]
	s_barrier
	s_and_saveexec_b64 s[8:9], s[4:5]
	s_cbranch_execz .LBB0_2005
	s_add_i32 s1, s95, s0
	v_add_u32_e32 v5, s1, v173
	ds_read_b128 v[6:9], v5
	v_fma_f32 v10, -v132, v0, -v131
	v_fma_f32 v80, 0, v132, v10
	v_add_f32_e32 v81, v132, v10
	v_fma_f32 v82, v140, s22, v10
	v_fma_f32 v83, v141, s23, v10
	v_fma_f32 v84, v140, s24, v10
	v_fma_f32 v85, v141, s25, v10
	v_fma_f32 v86, v140, s26, v10
	v_fma_f32 v87, v141, s27, v10
	v_fma_f32 v88, v140, s28, v10
	v_fma_f32 v89, v141, s29, v10
	v_fma_f32 v90, v140, s30, v10
	v_fma_f32 v91, v141, s31, v10
	v_fma_f32 v92, v140, s34, v10
	v_fma_f32 v93, v141, s35, v10
	v_fma_f32 v94, v140, s36, v10
	v_fma_f32 v95, v141, s37, v10
	v_add_u32_e32 v11, s1, v175
	v_add_u32_e32 v12, s1, v176
	s_waitcnt lgkmcnt(0)
	v_mfma_f32_32x32x16_bf16 v[80:95], v[6:9], v[112:115], v[80:95]
	ds_read_b128 v[6:9], v11
	v_add_u32_e32 v13, s1, v174
	v_mov_b32_e32 v133, v132
	v_fma_f32 v110, v132, s38, v10
	v_fma_f32 v111, v133, s39, v10
	v_fma_f32 v108, v132, s40, v10
	v_fma_f32 v109, v133, s41, v10
	v_fma_f32 v106, v132, s42, v10
	v_fma_f32 v107, v133, s43, v10
	v_fma_f32 v104, v132, s44, v10
	v_fma_f32 v105, v133, s45, v10
	s_waitcnt lgkmcnt(0)
	v_mfma_f32_32x32x16_bf16 v[80:95], v[6:9], v[116:119], v[80:95]
	ds_read_b128 v[6:9], v12
	v_fma_f32 v102, v132, s46, v10
	v_fma_f32 v103, v133, s47, v10
	v_fma_f32 v100, v132, s48, v10
	v_fma_f32 v101, v133, s49, v10
	v_fma_f32 v98, v132, s50, v10
	v_fma_f32 v99, v133, s51, v10
	v_fma_f32 v96, v142, s52, v10
	v_fma_f32 v97, v143, s53, v10
	s_waitcnt lgkmcnt(0)
	v_mfma_f32_32x32x16_bf16 v[80:95], v[6:9], v[120:123], v[80:95]
	ds_read_b128 v[6:9], v13
	s_waitcnt lgkmcnt(0)
	v_mfma_f32_32x32x16_bf16 v[80:95], v[6:9], v[124:127], v[80:95]
	ds_read_b128 v[6:9], v5 offset:4096
	s_waitcnt lgkmcnt(0)
	v_mfma_f32_32x32x16_bf16 v[96:111], v[6:9], v[112:115], v[96:111]
	ds_read_b128 v[6:9], v11 offset:4096
	s_waitcnt lgkmcnt(0)
	v_mfma_f32_32x32x16_bf16 v[96:111], v[6:9], v[116:119], v[96:111]
	ds_read_b128 v[6:9], v12 offset:4096
	s_waitcnt lgkmcnt(0)
	v_mfma_f32_32x32x16_bf16 v[96:111], v[6:9], v[120:123], v[96:111]
	ds_read_b128 v[6:9], v13 offset:4096
	s_waitcnt lgkmcnt(0)
	v_mfma_f32_32x32x16_bf16 v[96:111], v[6:9], v[124:127], v[96:111]

; #define MFMA(a, b, c) __builtin_amdgcn_mfma_f32_32x32x16_bf16((a), (b), (c), 0, 0, 0)
; DI void qk_acc(f32x16 (&st)[2], const bf16x8 (&qf)[4], const char* sb, const int (&foff)[4]) {
; #pragma unroll
;   for (int kb = 0; kb < 2; ++kb)
; #pragma unroll
;     for (int ks = 0; ks < 4; ++ks) {
;       const bf16x8 kf = *(const bf16x8*)(sb + kb * 4096 + foff[ks]);
;       st[kb] = MFMA(kf, qf[ks], st[kb]);
;     }
; }
; template <int DV, bool SEL, bool TERM> ...
;     ...
;     const int dmax = wq_max - kp_mul * k0, dmin = wq_min - kp_mul * (k0 + 63);
;     const bool relevant = !(dmax < 0 || dmin >= W) && !(TERM && done);
;     const float dbase = (float)(tqp - kp_mul * (k0 + 4 * h));
;     f32x16 st[2];
;     if (relevant) {
;       const float tb = -slope2 * dbase - mref;
; #pragma unroll
;       for (int kb = 0; kb < 2; ++kb)
; #pragma unroll
;         for (int i = 0; i < 16; ++i) st[kb][i] = __builtin_fmaf(sk, (float)(kb * 32 + (i & 3) + 8 * (i >> 2)), tb);
;       qk_acc(st, qf, sb, foff);
.LBB0_2092:
	s_lshl_b32 s1, s8, 6
	v_or_b32_e32 v0, s1, v174
	v_sub_u32_e32 v2, v159, v0
	s_or_b32 s4, s1, 63
	v_cvt_f32_i32_e32 v0, v2
	s_mul_hi_u32 s0, s96, 0xaaaaaaab
	s_waitcnt lgkmcnt(0)
	v_subrev_u32_e32 v3, s1, v161
	v_subrev_u32_e32 v4, s4, v160
	s_lshr_b32 s0, s0, 1
	v_cmp_lt_i32_e32 vcc, -1, v3
	v_cmp_gt_i32_e64 s[4:5], s97, v4
	s_mul_i32 s0, s0, 0xfffee000
	s_and_b64 s[4:5], vcc, s[4:5]
	s_barrier
	s_and_saveexec_b64 s[8:9], s[4:5]
	s_cbranch_execz .LBB0_2094
	s_add_i32 s1, s19, s0
	v_add_u32_e32 v5, s1, v181
	ds_read_b128 v[6:9], v5
	v_fma_f32 v10, -v136, v0, -v156
	v_fma_f32 v80, 0, v136, v10
	v_add_f32_e32 v81, v136, v10
	v_fma_f32 v82, v144, s24, v10
	v_fma_f32 v83, v145, s25, v10
	v_fma_f32 v84, v144, s26, v10
	v_fma_f32 v85, v145, s27, v10
	v_fma_f32 v86, v144, s28, v10
	v_fma_f32 v87, v145, s29, v10
	v_fma_f32 v88, v144, s30, v10
	v_fma_f32 v89, v145, s31, v10
	v_fma_f32 v90, v144, s34, v10
	v_fma_f32 v91, v145, s35, v10
	v_fma_f32 v92, v144, s36, v10
	v_fma_f32 v93, v145, s37, v10
	v_fma_f32 v94, v144, s38, v10
	v_fma_f32 v95, v145, s39, v10
	v_add_u32_e32 v11, s1, v183
	v_add_u32_e32 v12, s1, v184
	s_waitcnt lgkmcnt(0)
	v_mfma_f32_32x32x16_bf16 v[80:95], v[6:9], v[112:115], v[80:95]
	ds_read_b128 v[6:9], v11
	v_add_u32_e32 v13, s1, v182
	v_mov_b32_e32 v137, v136
	v_fma_f32 v110, v136, s40, v10
	v_fma_f32 v111, v137, s41, v10
	v_fma_f32 v108, v136, s42, v10
	v_fma_f32 v109, v137, s43, v10
	v_fma_f32 v106, v136, s44, v10
	v_fma_f32 v107, v137, s45, v10
	v_fma_f32 v104, v136, s46, v10
	v_fma_f32 v105, v137, s47, v10
	s_waitcnt lgkmcnt(0)
	v_mfma_f32_32x32x16_bf16 v[80:95], v[6:9], v[116:119], v[80:95]
	ds_read_b128 v[6:9], v12
	v_fma_f32 v102, v136, s48, v10
	v_fma_f32 v103, v137, s49, v10
	v_fma_f32 v100, v136, s50, v10
	v_fma_f32 v101, v137, s51, v10
	v_fma_f32 v98, v136, s52, v10
	v_fma_f32 v99, v137, s53, v10
	v_fma_f32 v96, v146, s54, v10
	v_fma_f32 v97, v147, s55, v10
	s_waitcnt lgkmcnt(0)
	v_mfma_f32_32x32x16_bf16 v[80:95], v[6:9], v[120:123], v[80:95]
	ds_read_b128 v[6:9], v13
	s_waitcnt lgkmcnt(0)
	v_mfma_f32_32x32x16_bf16 v[80:95], v[6:9], v[124:127], v[80:95]
	ds_read_b128 v[6:9], v5 offset:4096
	s_waitcnt lgkmcnt(0)
	v_mfma_f32_32x32x16_bf16 v[96:111], v[6:9], v[112:115], v[96:111]
	ds_read_b128 v[6:9], v11 offset:4096
	s_waitcnt lgkmcnt(0)
	v_mfma_f32_32x32x16_bf16 v[96:111], v[6:9], v[116:119], v[96:111]
	ds_read_b128 v[6:9], v12 offset:4096
	s_waitcnt lgkmcnt(0)
	v_mfma_f32_32x32x16_bf16 v[96:111], v[6:9], v[120:123], v[96:111]
	ds_read_b128 v[6:9], v13 offset:4096
	s_waitcnt lgkmcnt(0)
	v_mfma_f32_32x32x16_bf16 v[96:111], v[6:9], v[124:127], v[96:111]

; #define MFMA(a, b, c) __builtin_amdgcn_mfma_f32_32x32x16_bf16((a), (b), (c), 0, 0, 0)
; DI void qk_acc(f32x16 (&st)[2], const bf16x8 (&qf)[4], const char* sb, const int (&foff)[4]) {
; #pragma unroll
;   for (int kb = 0; kb < 2; ++kb)
; #pragma unroll
;     for (int ks = 0; ks < 4; ++ks) {
;       const bf16x8 kf = *(const bf16x8*)(sb + kb * 4096 + foff[ks]);
;       st[kb] = MFMA(kf, qf[ks], st[kb]);
;     }
; }
; template <int DV, bool SEL, bool TERM> ...
;     ...
;     const int dmax = wq_max - kp_mul * k0, dmin = wq_min - kp_mul * (k0 + 63);
;     const bool relevant = !(dmax < 0 || dmin >= W) && !(TERM && done);
;     const float dbase = (float)(tqp - kp_mul * (k0 + 4 * h));
;     f32x16 st[2];
;     if (relevant) {
;       const float tb = -slope2 * dbase - mref;
; #pragma unroll
;       for (int kb = 0; kb < 2; ++kb)
; #pragma unroll
;         for (int i = 0; i < 16; ++i) st[kb][i] = __builtin_fmaf(sk, (float)(kb * 32 + (i & 3) + 8 * (i >> 2)), tb);
;       qk_acc(st, qf, sb, foff);
.LBB0_2116:
	s_lshl_b32 s1, s8, 6
	v_or_b32_e32 v0, s1, v158
	v_sub_u32_e32 v116, v134, v0
	s_or_b32 s4, s1, 63
	v_cvt_f32_i32_e32 v0, v116
	s_mul_hi_u32 s0, s19, 0xaaaaaaab
	s_waitcnt lgkmcnt(0)
	v_subrev_u32_e32 v117, s1, v136
	v_subrev_u32_e32 v118, s4, v135
	s_lshr_b32 s0, s0, 1
	v_cmp_lt_i32_e32 vcc, -1, v117
	v_cmp_gt_i32_e64 s[4:5], s97, v118
	s_mul_i32 s0, s0, 0xfffee000
	s_and_b64 s[4:5], vcc, s[4:5]
	s_barrier
	s_and_saveexec_b64 s[8:9], s[4:5]
	s_cbranch_execz .LBB0_2118
	s_add_i32 s1, s17, s0
	v_add_u32_e32 v119, s1, v165
	ds_read_b128 v[96:99], v119
	v_fma_f32 v170, -v14, v0, -v156
	v_fma_f32 v80, 0, v14, v170
	v_add_f32_e32 v81, v14, v170
	v_fma_f32 v82, v126, s24, v170
	v_fma_f32 v83, v127, s25, v170
	v_fma_f32 v84, v126, s26, v170
	v_fma_f32 v85, v127, s27, v170
	v_fma_f32 v86, v126, s28, v170
	v_fma_f32 v87, v127, s29, v170
	v_fma_f32 v88, v126, s30, v170
	v_fma_f32 v89, v127, s31, v170
	v_fma_f32 v90, v126, s34, v170
	v_fma_f32 v91, v127, s35, v170
	v_fma_f32 v92, v126, s36, v170
	v_fma_f32 v93, v127, s37, v170
	v_fma_f32 v94, v126, s38, v170
	v_fma_f32 v95, v127, s39, v170
	v_add_u32_e32 v169, s1, v167
	v_add_u32_e32 v174, s1, v168
	s_waitcnt lgkmcnt(0)
	v_mfma_f32_32x32x16_bf16 v[80:95], v[96:99], v[2:5], v[80:95]
	ds_read_b128 v[96:99], v169
	v_add_u32_e32 v175, s1, v166
	v_mov_b32_e32 v15, v14
	v_fma_f32 v110, v14, s40, v170
	v_fma_f32 v111, v15, s41, v170
	v_fma_f32 v108, v14, s42, v170
	v_fma_f32 v109, v15, s43, v170
	v_fma_f32 v106, v14, s44, v170
	v_fma_f32 v107, v15, s45, v170
	v_fma_f32 v104, v14, s46, v170
	v_fma_f32 v105, v15, s47, v170
	s_waitcnt lgkmcnt(0)
	v_mfma_f32_32x32x16_bf16 v[80:95], v[96:99], v[6:9], v[80:95]
	ds_read_b128 v[96:99], v174
	v_fma_f32 v102, v14, s48, v170
	v_fma_f32 v103, v15, s49, v170
	v_fma_f32 v100, v14, s50, v170
	v_fma_f32 v101, v15, s51, v170
	s_waitcnt lgkmcnt(0)
	v_mfma_f32_32x32x16_bf16 v[80:95], v[96:99], v[10:13], v[80:95]
	ds_read_b128 v[96:99], v175
	s_waitcnt lgkmcnt(0)
	v_mfma_f32_32x32x16_bf16 v[80:95], v[96:99], v[112:115], v[80:95]
	v_fma_f32 v98, v14, s52, v170
	v_fma_f32 v99, v15, s53, v170
	v_fma_f32 v96, v132, s54, v170
	v_fma_f32 v97, v133, s55, v170
	ds_read_b128 v[170:173], v119 offset:4096
	s_waitcnt lgkmcnt(0)
	v_mfma_f32_32x32x16_bf16 v[96:111], v[170:173], v[2:5], v[96:111]
	ds_read_b128 v[170:173], v169 offset:4096
	s_waitcnt lgkmcnt(0)
	v_mfma_f32_32x32x16_bf16 v[96:111], v[170:173], v[6:9], v[96:111]
	ds_read_b128 v[170:173], v174 offset:4096
	s_waitcnt lgkmcnt(0)
	v_mfma_f32_32x32x16_bf16 v[96:111], v[170:173], v[10:13], v[96:111]
	ds_read_b128 v[170:173], v175 offset:4096
	s_waitcnt lgkmcnt(0)
	v_mfma_f32_32x32x16_bf16 v[96:111], v[170:173], v[112:115], v[96:111]
